# v24 + sample-chain output tail: the four serialized gain/gate loads (each behind s_waitcnt vmcnt(0)) issued together, one wait
# speedup vs baseline: 1.0057x; 1.0057x over previous
.LBB0_1192:
	s_and_b32 s4, s7, -4
	s_and_b32 s1, s6, 0x180
	s_waitcnt lgkmcnt(0)
	s_add_i32 s0, s90, s7
	s_add_i32 s2, s4, 0x4000
	s_lshl_b32 s1, s1, 1
	s_mul_i32 s5, s4, 0x1600
	s_add_u32 s8, s52, s1
	s_addc_u32 s9, s53, 0
	s_mul_hi_i32 s3, s2, 0x1600
	s_add_i32 s2, s5, 0x5800000
	s_add_u32 s2, s8, s2
	s_waitcnt vmcnt(9)
	v_lshl_add_u64 v[0:1], v[132:133], 0, v[130:131]
	s_addc_u32 s3, s9, s3
	global_load_dwordx4 v[154:157], v[0:1], off
	global_load_dwordx4 v[168:171], v[0:1], off offset:512
	global_load_dwordx4 v[118:121], v[0:1], off offset:1024
	global_load_dwordx4 v[114:117], v[0:1], off offset:1536
	global_load_dwordx4 v[110:113], v[0:1], off offset:2048
	global_load_dwordx4 v[106:109], v[0:1], off offset:2560
	global_load_dwordx4 v[94:97], v[0:1], off offset:3072
	global_load_dwordx4 v[90:93], v[0:1], off offset:3584
	v_lshl_add_u64 v[0:1], s[2:3], 0, v[136:137]
	global_load_dwordx4 v[98:101], v[0:1], off offset:2560
	global_load_dwordx4 v[102:105], v[0:1], off offset:1536
	global_load_dwordx2 v[152:153], v166, s[2:3] offset:3584
	s_add_i32 s2, s4, 0x4001
	s_mul_hi_i32 s3, s2, 0x1600
	s_add_i32 s2, s5, 0x5801600
	s_add_u32 s2, s8, s2
	s_addc_u32 s3, s9, s3
	v_lshl_add_u64 v[0:1], s[2:3], 0, v[136:137]
	global_load_dwordx4 v[82:85], v[0:1], off offset:2560
	global_load_dwordx4 v[86:89], v[0:1], off offset:1536
	global_load_dwordx2 v[150:151], v166, s[2:3] offset:3584
	s_add_i32 s2, s4, 0x4002
	s_mul_hi_i32 s3, s2, 0x1600
	s_add_i32 s2, s5, 0x5802c00
	s_add_u32 s2, s8, s2
	s_addc_u32 s3, s9, s3
	v_lshl_add_u64 v[0:1], s[2:3], 0, v[136:137]
	global_load_dwordx4 v[74:77], v[0:1], off offset:2560
	global_load_dwordx4 v[78:81], v[0:1], off offset:1536
	global_load_dwordx2 v[148:149], v166, s[2:3] offset:3584
	s_add_i32 s2, s4, 0x4003
	s_add_i32 s5, s5, 0x5804200
	s_mul_hi_i32 s3, s2, 0x1600
	s_add_u32 s2, s8, s5
	s_addc_u32 s3, s9, s3
	v_lshl_add_u64 v[0:1], s[2:3], 0, v[136:137]
	s_cmpk_lt_i32 s0, 0x200
	global_load_dwordx4 v[66:69], v[0:1], off offset:2560
	global_load_dwordx4 v[70:73], v[0:1], off offset:1536
	global_load_dwordx2 v[146:147], v166, s[2:3] offset:3584
	s_cselect_b64 s[2:3], -1, 0
	s_and_b64 s[8:9], s[2:3], exec
	s_cselect_b32 s8, s0, 0x1ff
	s_ashr_i32 s9, s8, 31
	s_lshl_b64 s[10:11], s[8:9], 16
	s_and_b32 s5, s8, -4
	s_lshl_b32 s8, s8, 8
	s_add_i32 s9, s5, 0x4000
	s_and_b32 s8, s8, 0x300
	v_lshl_add_u64 v[0:1], v[122:123], 0, s[10:11]
	s_mul_i32 s10, s5, 0x1600
	s_add_u32 s11, s52, s8
	s_addc_u32 s12, s53, 0
	s_add_i32 s8, s10, 0x5800000
	s_mul_hi_i32 s9, s9, 0x1600
	s_add_u32 s8, s11, s8
	s_addc_u32 s9, s12, s9
	global_load_dwordx4 v[62:65], v[0:1], off
	global_load_dwordx4 v[58:61], v[0:1], off offset:512
	global_load_dwordx4 v[54:57], v[0:1], off offset:1024
	global_load_dwordx4 v[50:53], v[0:1], off offset:1536
	global_load_dwordx4 v[46:49], v[0:1], off offset:2048
	global_load_dwordx4 v[42:45], v[0:1], off offset:2560
	global_load_dwordx4 v[30:33], v[0:1], off offset:3072
	global_load_dwordx4 v[26:29], v[0:1], off offset:3584
	v_lshl_add_u64 v[0:1], s[8:9], 0, v[136:137]
	global_load_dwordx4 v[38:41], v[0:1], off offset:2560
	global_load_dwordx4 v[34:37], v[0:1], off offset:1536
	global_load_dwordx2 v[144:145], v166, s[8:9] offset:3584
	s_add_i32 s8, s5, 0x4001
	s_mul_hi_i32 s9, s8, 0x1600
	s_add_i32 s8, s10, 0x5801600
	s_add_u32 s8, s11, s8
	s_addc_u32 s9, s12, s9
	v_lshl_add_u64 v[0:1], s[8:9], 0, v[136:137]
	global_load_dwordx4 v[22:25], v[0:1], off offset:2560
	global_load_dwordx4 v[18:21], v[0:1], off offset:1536
	global_load_dwordx2 v[142:143], v166, s[8:9] offset:3584
	s_add_i32 s8, s5, 0x4002
	s_mul_hi_i32 s9, s8, 0x1600
	s_add_i32 s8, s10, 0x5802c00
	s_add_u32 s8, s11, s8
	s_addc_u32 s9, s12, s9
	v_lshl_add_u64 v[0:1], s[8:9], 0, v[136:137]
	s_addk_i32 s5, 0x4003
	s_add_i32 s10, s10, 0x5804200
	global_load_dwordx4 v[12:15], v[0:1], off offset:2560
	global_load_dwordx4 v[8:11], v[0:1], off offset:1536
	global_load_dwordx2 v[140:141], v166, s[8:9] offset:3584
	s_mul_hi_i32 s5, s5, 0x1600
	s_add_u32 s8, s11, s10
	s_addc_u32 s9, s12, s5
	v_lshl_add_u64 v[0:1], s[8:9], 0, v[136:137]
	global_load_dwordx4 v[4:7], v[0:1], off offset:2560
	s_nop 0
	global_load_dwordx4 v[0:3], v[0:1], off offset:1536
	s_nop 0
	global_load_dwordx2 v[138:139], v166, s[8:9] offset:3584
	v_readfirstlane_b32 s5, v17
	s_ashr_i32 s5, s5, 6
	s_cmp_gt_i32 s5, 3
	s_waitcnt vmcnt(30)
	v_lshlrev_b32_e32 v158, 16, v102
	s_waitcnt vmcnt(29)
	v_lshlrev_b32_e32 v160, 16, v152
	v_and_b32_e32 v161, 0xffff0000, v152
	v_lshlrev_b32_e32 v152, 16, v98
	v_exp_f32_e32 v172, v152
	v_lshlrev_b32_e32 v162, 16, v153
	v_and_b32_e32 v163, 0xffff0000, v153
	v_sub_f32_e32 v152, 1.0, v172
	v_pk_mul_f32 v[174:175], v[152:153], v[160:161] op_sel_hi:[0,1]
	v_pk_mul_f32 v[152:153], v[152:153], v[162:163] op_sel_hi:[0,1]
	v_pk_fma_f32 v[152:153], v[156:157], v[172:173], v[152:153] op_sel_hi:[1,0,1]
	v_and_b32_e32 v156, 0xffff0000, v98
	v_and_b32_e32 v98, 0xffff0000, v102
	v_exp_f32_e32 v102, v156
	v_pk_fma_f32 v[154:155], v[154:155], v[172:173], v[174:175] op_sel_hi:[1,0,1]
	v_pk_fma_f32 v[174:175], v[158:159], v[152:153], 0 op_sel_hi:[0,1,0]
	v_pk_fma_f32 v[172:173], v[158:159], v[154:155], 0 op_sel_hi:[0,1,0]
	v_sub_f32_e32 v156, 1.0, v102
	v_pk_mul_f32 v[158:159], v[156:157], v[162:163] op_sel_hi:[0,1]
	v_pk_mul_f32 v[156:157], v[156:157], v[160:161] op_sel_hi:[0,1]
	v_pk_fma_f32 v[156:157], v[168:169], v[102:103], v[156:157] op_sel_hi:[1,0,1]
	v_pk_fma_f32 v[158:159], v[170:171], v[102:103], v[158:159] op_sel_hi:[1,0,1]
	v_lshlrev_b32_e32 v102, 16, v99
	v_exp_f32_e32 v102, v102
	v_pk_fma_f32 v[170:171], v[98:99], v[156:157], v[172:173] op_sel_hi:[0,1,1]
	v_pk_fma_f32 v[168:169], v[98:99], v[158:159], v[174:175] op_sel_hi:[0,1,1]
	v_lshlrev_b32_e32 v98, 16, v103
	v_sub_f32_e32 v172, 1.0, v102
	v_pk_mul_f32 v[174:175], v[172:173], v[160:161] op_sel_hi:[0,1]
	v_pk_mul_f32 v[172:173], v[172:173], v[162:163] op_sel_hi:[0,1]
	v_pk_fma_f32 v[120:121], v[120:121], v[102:103], v[172:173] op_sel_hi:[1,0,1]
	v_pk_fma_f32 v[118:119], v[118:119], v[102:103], v[174:175] op_sel_hi:[1,0,1]
	v_pk_fma_f32 v[168:169], v[98:99], v[120:121], v[168:169] op_sel_hi:[0,1,1]
	v_pk_fma_f32 v[170:171], v[98:99], v[118:119], v[170:171] op_sel_hi:[0,1,1]
	v_and_b32_e32 v98, 0xffff0000, v99
	v_exp_f32_e32 v102, v98
	v_and_b32_e32 v172, 0xffff0000, v103
	v_sub_f32_e32 v98, 1.0, v102
	v_pk_mul_f32 v[174:175], v[98:99], v[162:163] op_sel_hi:[0,1]
	v_pk_mul_f32 v[98:99], v[98:99], v[160:161] op_sel_hi:[0,1]
	v_pk_fma_f32 v[98:99], v[114:115], v[102:103], v[98:99] op_sel_hi:[1,0,1]
	v_pk_fma_f32 v[102:103], v[116:117], v[102:103], v[174:175] op_sel_hi:[1,0,1]
	v_pk_fma_f32 v[116:117], v[172:173], v[98:99], v[170:171] op_sel_hi:[0,1,1]
	v_pk_fma_f32 v[114:115], v[172:173], v[102:103], v[168:169] op_sel_hi:[0,1,1]
	v_lshlrev_b32_e32 v169, 16, v100
	v_exp_f32_e32 v170, v169
	v_lshlrev_b32_e32 v168, 16, v104
	v_sub_f32_e32 v172, 1.0, v170
	v_pk_mul_f32 v[174:175], v[172:173], v[160:161] op_sel_hi:[0,1]
	v_pk_mul_f32 v[172:173], v[172:173], v[162:163] op_sel_hi:[0,1]
	v_pk_fma_f32 v[112:113], v[112:113], v[170:171], v[172:173] op_sel_hi:[1,0,1]
	v_pk_fma_f32 v[110:111], v[110:111], v[170:171], v[174:175] op_sel_hi:[1,0,1]
	v_pk_fma_f32 v[114:115], v[168:169], v[112:113], v[114:115] op_sel_hi:[0,1,1]
	v_pk_fma_f32 v[116:117], v[168:169], v[110:111], v[116:117] op_sel_hi:[0,1,1]
	v_and_b32_e32 v168, 0xffff0000, v100
	v_and_b32_e32 v100, 0xffff0000, v104
	v_exp_f32_e32 v104, v168
	s_nop 0
	v_sub_f32_e32 v168, 1.0, v104
	v_pk_mul_f32 v[170:171], v[168:169], v[162:163] op_sel_hi:[0,1]
	v_pk_mul_f32 v[168:169], v[168:169], v[160:161] op_sel_hi:[0,1]
	v_pk_fma_f32 v[106:107], v[106:107], v[104:105], v[168:169] op_sel_hi:[1,0,1]
	v_pk_fma_f32 v[108:109], v[108:109], v[104:105], v[170:171] op_sel_hi:[1,0,1]
	v_lshlrev_b32_e32 v104, 16, v101
	v_exp_f32_e32 v104, v104
	v_pk_fma_f32 v[114:115], v[100:101], v[108:109], v[114:115] op_sel_hi:[0,1,1]
	v_pk_fma_f32 v[116:117], v[100:101], v[106:107], v[116:117] op_sel_hi:[0,1,1]
	v_lshlrev_b32_e32 v100, 16, v105
	v_sub_f32_e32 v168, 1.0, v104
	v_pk_mul_f32 v[170:171], v[168:169], v[160:161] op_sel_hi:[0,1]
	v_pk_mul_f32 v[168:169], v[168:169], v[162:163] op_sel_hi:[0,1]
	v_pk_fma_f32 v[96:97], v[96:97], v[104:105], v[168:169] op_sel_hi:[1,0,1]
	v_pk_fma_f32 v[94:95], v[94:95], v[104:105], v[170:171] op_sel_hi:[1,0,1]
	v_pk_fma_f32 v[114:115], v[100:101], v[96:97], v[114:115] op_sel_hi:[0,1,1]
	v_pk_fma_f32 v[168:169], v[100:101], v[94:95], v[116:117] op_sel_hi:[0,1,1]
	v_and_b32_e32 v101, 0xffff0000, v101
	v_exp_f32_e32 v104, v101
	v_and_b32_e32 v100, 0xffff0000, v105
	v_sub_f32_e32 v116, 1.0, v104
	v_pk_mul_f32 v[162:163], v[116:117], v[162:163] op_sel_hi:[0,1]
	v_pk_mul_f32 v[116:117], v[116:117], v[160:161] op_sel_hi:[0,1]
	v_pk_fma_f32 v[90:91], v[90:91], v[104:105], v[116:117] op_sel_hi:[1,0,1]
	v_pk_fma_f32 v[92:93], v[92:93], v[104:105], v[162:163] op_sel_hi:[1,0,1]
	s_waitcnt vmcnt(26)
	v_lshlrev_b32_e32 v160, 16, v150
	v_pk_fma_f32 v[116:117], v[100:101], v[92:93], v[114:115] op_sel_hi:[0,1,1]
	v_pk_fma_f32 v[114:115], v[100:101], v[90:91], v[168:169] op_sel_hi:[0,1,1]
	v_lshlrev_b32_e32 v100, 16, v82
	v_exp_f32_e32 v104, v100
	v_and_b32_e32 v161, 0xffff0000, v150
	v_lshlrev_b32_e32 v150, 16, v151
	v_and_b32_e32 v151, 0xffff0000, v151
	v_sub_f32_e32 v100, 1.0, v104
	ds_write_b128 v127, v[114:117]
	v_pk_mul_f32 v[116:117], v[100:101], v[160:161] op_sel_hi:[0,1]
	v_pk_mul_f32 v[100:101], v[100:101], v[150:151] op_sel_hi:[0,1]
	v_lshlrev_b32_e32 v114, 16, v86
	v_pk_fma_f32 v[100:101], v[104:105], v[152:153], v[100:101] op_sel_hi:[0,1,1]
	v_pk_fma_f32 v[104:105], v[104:105], v[154:155], v[116:117] op_sel_hi:[0,1,1]
	v_pk_fma_f32 v[152:153], v[114:115], v[104:105], 0 op_sel_hi:[0,1,0]
	v_pk_fma_f32 v[154:155], v[114:115], v[100:101], 0 op_sel_hi:[0,1,0]
	v_and_b32_e32 v114, 0xffff0000, v82
	v_and_b32_e32 v82, 0xffff0000, v86
	v_exp_f32_e32 v86, v114
	s_nop 0
	v_sub_f32_e32 v114, 1.0, v86
	v_pk_mul_f32 v[116:117], v[114:115], v[150:151] op_sel_hi:[0,1]
	v_pk_mul_f32 v[114:115], v[114:115], v[160:161] op_sel_hi:[0,1]
	v_pk_fma_f32 v[114:115], v[86:87], v[156:157], v[114:115] op_sel_hi:[0,1,1]
	v_pk_fma_f32 v[116:117], v[86:87], v[158:159], v[116:117] op_sel_hi:[0,1,1]
	v_lshlrev_b32_e32 v86, 16, v83
	v_exp_f32_e32 v86, v86
	v_pk_fma_f32 v[154:155], v[82:83], v[116:117], v[154:155] op_sel_hi:[0,1,1]
	v_pk_fma_f32 v[152:153], v[82:83], v[114:115], v[152:153] op_sel_hi:[0,1,1]
	v_lshlrev_b32_e32 v82, 16, v87
	v_sub_f32_e32 v156, 1.0, v86
	v_pk_mul_f32 v[158:159], v[156:157], v[160:161] op_sel_hi:[0,1]
	v_pk_mul_f32 v[156:157], v[156:157], v[150:151] op_sel_hi:[0,1]
	v_pk_fma_f32 v[120:121], v[86:87], v[120:121], v[156:157] op_sel_hi:[0,1,1]
	v_pk_fma_f32 v[118:119], v[86:87], v[118:119], v[158:159] op_sel_hi:[0,1,1]
	v_pk_fma_f32 v[152:153], v[82:83], v[118:119], v[152:153] op_sel_hi:[0,1,1]
	v_pk_fma_f32 v[154:155], v[82:83], v[120:121], v[154:155] op_sel_hi:[0,1,1]
	v_and_b32_e32 v83, 0xffff0000, v83
	v_exp_f32_e32 v156, v83
	v_and_b32_e32 v82, 0xffff0000, v87
	v_sub_f32_e32 v86, 1.0, v156
	v_pk_mul_f32 v[158:159], v[86:87], v[150:151] op_sel_hi:[0,1]
	v_pk_mul_f32 v[86:87], v[86:87], v[160:161] op_sel_hi:[0,1]
	v_pk_fma_f32 v[86:87], v[156:157], v[98:99], v[86:87] op_sel_hi:[0,1,1]
	v_pk_fma_f32 v[98:99], v[156:157], v[102:103], v[158:159] op_sel_hi:[0,1,1]
	v_lshlrev_b32_e32 v102, 16, v84
	v_exp_f32_e32 v156, v102
	v_pk_fma_f32 v[154:155], v[82:83], v[98:99], v[154:155] op_sel_hi:[0,1,1]
	v_pk_fma_f32 v[82:83], v[82:83], v[86:87], v[152:153] op_sel_hi:[0,1,1]
	v_lshlrev_b32_e32 v152, 16, v88
	v_sub_f32_e32 v102, 1.0, v156
	v_pk_mul_f32 v[158:159], v[102:103], v[160:161] op_sel_hi:[0,1]
	v_pk_mul_f32 v[102:103], v[102:103], v[150:151] op_sel_hi:[0,1]
	v_pk_fma_f32 v[102:103], v[156:157], v[112:113], v[102:103] op_sel_hi:[0,1,1]
	v_pk_fma_f32 v[110:111], v[156:157], v[110:111], v[158:159] op_sel_hi:[0,1,1]
	v_pk_fma_f32 v[82:83], v[152:153], v[110:111], v[82:83] op_sel_hi:[0,1,1]
	v_pk_fma_f32 v[112:113], v[152:153], v[102:103], v[154:155] op_sel_hi:[0,1,1]
	v_and_b32_e32 v152, 0xffff0000, v84
	v_and_b32_e32 v84, 0xffff0000, v88
	v_exp_f32_e32 v88, v152
	s_nop 0
	v_sub_f32_e32 v152, 1.0, v88
	v_pk_mul_f32 v[154:155], v[152:153], v[150:151] op_sel_hi:[0,1]
	v_pk_mul_f32 v[152:153], v[152:153], v[160:161] op_sel_hi:[0,1]
	v_pk_fma_f32 v[106:107], v[88:89], v[106:107], v[152:153] op_sel_hi:[0,1,1]
	v_pk_fma_f32 v[108:109], v[88:89], v[108:109], v[154:155] op_sel_hi:[0,1,1]
	v_lshlrev_b32_e32 v88, 16, v85
	v_exp_f32_e32 v88, v88
	v_pk_fma_f32 v[112:113], v[84:85], v[108:109], v[112:113] op_sel_hi:[0,1,1]
	v_pk_fma_f32 v[82:83], v[84:85], v[106:107], v[82:83] op_sel_hi:[0,1,1]
	v_lshlrev_b32_e32 v84, 16, v89
	v_sub_f32_e32 v152, 1.0, v88
	v_pk_mul_f32 v[154:155], v[152:153], v[160:161] op_sel_hi:[0,1]
	v_pk_mul_f32 v[152:153], v[152:153], v[150:151] op_sel_hi:[0,1]
	v_pk_fma_f32 v[96:97], v[88:89], v[96:97], v[152:153] op_sel_hi:[0,1,1]
	v_pk_fma_f32 v[94:95], v[88:89], v[94:95], v[154:155] op_sel_hi:[0,1,1]
	v_pk_fma_f32 v[82:83], v[84:85], v[94:95], v[82:83] op_sel_hi:[0,1,1]
	v_pk_fma_f32 v[112:113], v[84:85], v[96:97], v[112:113] op_sel_hi:[0,1,1]
	v_and_b32_e32 v84, 0xffff0000, v85
	v_exp_f32_e32 v84, v84
	v_and_b32_e32 v152, 0xffff0000, v89
	v_sub_f32_e32 v88, 1.0, v84
	v_pk_mul_f32 v[150:151], v[88:89], v[150:151] op_sel_hi:[0,1]
	v_pk_mul_f32 v[88:89], v[88:89], v[160:161] op_sel_hi:[0,1]
	v_pk_fma_f32 v[88:89], v[84:85], v[90:91], v[88:89] op_sel_hi:[0,1,1]
	v_pk_fma_f32 v[90:91], v[84:85], v[92:93], v[150:151] op_sel_hi:[0,1,1]
	v_pk_fma_f32 v[84:85], v[152:153], v[90:91], v[112:113] op_sel_hi:[0,1,1]
	v_pk_fma_f32 v[82:83], v[152:153], v[88:89], v[82:83] op_sel_hi:[0,1,1]
	ds_write_b128 v127, v[82:85] offset:8192
	s_waitcnt vmcnt(25)
	v_lshlrev_b32_e32 v83, 16, v74
	v_exp_f32_e32 v84, v83
	s_waitcnt vmcnt(23)
	v_lshlrev_b32_e32 v150, 16, v148
	v_and_b32_e32 v151, 0xffff0000, v148
	v_lshlrev_b32_e32 v148, 16, v149
	v_and_b32_e32 v149, 0xffff0000, v149
	v_sub_f32_e32 v92, 1.0, v84
	v_pk_mul_f32 v[112:113], v[92:93], v[150:151] op_sel_hi:[0,1]
	v_pk_mul_f32 v[92:93], v[92:93], v[148:149] op_sel_hi:[0,1]
	v_lshlrev_b32_e32 v82, 16, v78
	v_pk_fma_f32 v[92:93], v[84:85], v[100:101], v[92:93] op_sel_hi:[0,1,1]
	v_pk_fma_f32 v[100:101], v[84:85], v[104:105], v[112:113] op_sel_hi:[0,1,1]
	v_pk_fma_f32 v[84:85], v[82:83], v[100:101], 0 op_sel_hi:[0,1,0]
	v_pk_fma_f32 v[104:105], v[82:83], v[92:93], 0 op_sel_hi:[0,1,0]
	v_and_b32_e32 v82, 0xffff0000, v74
	v_and_b32_e32 v74, 0xffff0000, v78
	v_exp_f32_e32 v78, v82
	s_nop 0
	v_sub_f32_e32 v82, 1.0, v78
	v_pk_mul_f32 v[112:113], v[82:83], v[148:149] op_sel_hi:[0,1]
	v_pk_mul_f32 v[82:83], v[82:83], v[150:151] op_sel_hi:[0,1]
	v_pk_fma_f32 v[82:83], v[78:79], v[114:115], v[82:83] op_sel_hi:[0,1,1]
	v_pk_fma_f32 v[114:115], v[78:79], v[116:117], v[112:113] op_sel_hi:[0,1,1]
	v_lshlrev_b32_e32 v78, 16, v75
	v_exp_f32_e32 v78, v78
	v_pk_fma_f32 v[116:117], v[74:75], v[114:115], v[104:105] op_sel_hi:[0,1,1]
	v_pk_fma_f32 v[84:85], v[74:75], v[82:83], v[84:85] op_sel_hi:[0,1,1]
	v_lshlrev_b32_e32 v74, 16, v79
	v_sub_f32_e32 v104, 1.0, v78
	v_pk_mul_f32 v[112:113], v[104:105], v[150:151] op_sel_hi:[0,1]
	v_pk_mul_f32 v[104:105], v[104:105], v[148:149] op_sel_hi:[0,1]
	v_pk_fma_f32 v[104:105], v[78:79], v[120:121], v[104:105] op_sel_hi:[0,1,1]
	v_pk_fma_f32 v[112:113], v[78:79], v[118:119], v[112:113] op_sel_hi:[0,1,1]
	v_pk_fma_f32 v[84:85], v[74:75], v[112:113], v[84:85] op_sel_hi:[0,1,1]
	v_pk_fma_f32 v[118:119], v[74:75], v[104:105], v[116:117] op_sel_hi:[0,1,1]
	v_and_b32_e32 v75, 0xffff0000, v75
	v_exp_f32_e32 v116, v75
	v_and_b32_e32 v74, 0xffff0000, v79
	v_sub_f32_e32 v78, 1.0, v116
	v_pk_mul_f32 v[120:121], v[78:79], v[148:149] op_sel_hi:[0,1]
	v_pk_mul_f32 v[78:79], v[78:79], v[150:151] op_sel_hi:[0,1]
	v_pk_fma_f32 v[78:79], v[116:117], v[86:87], v[78:79] op_sel_hi:[0,1,1]
	v_pk_fma_f32 v[116:117], v[116:117], v[98:99], v[120:121] op_sel_hi:[0,1,1]
	v_pk_fma_f32 v[118:119], v[74:75], v[116:117], v[118:119] op_sel_hi:[0,1,1]
	v_pk_fma_f32 v[74:75], v[74:75], v[78:79], v[84:85] op_sel_hi:[0,1,1]
	v_lshlrev_b32_e32 v85, 16, v76
	v_exp_f32_e32 v98, v85
	v_lshlrev_b32_e32 v84, 16, v80
	v_sub_f32_e32 v86, 1.0, v98
	v_pk_mul_f32 v[120:121], v[86:87], v[150:151] op_sel_hi:[0,1]
	v_pk_mul_f32 v[86:87], v[86:87], v[148:149] op_sel_hi:[0,1]
	v_pk_fma_f32 v[86:87], v[98:99], v[102:103], v[86:87] op_sel_hi:[0,1,1]
	v_pk_fma_f32 v[98:99], v[98:99], v[110:111], v[120:121] op_sel_hi:[0,1,1]
	v_pk_fma_f32 v[74:75], v[84:85], v[98:99], v[74:75] op_sel_hi:[0,1,1]
	v_pk_fma_f32 v[110:111], v[84:85], v[86:87], v[118:119] op_sel_hi:[0,1,1]
	v_and_b32_e32 v84, 0xffff0000, v76
	v_and_b32_e32 v76, 0xffff0000, v80
	v_exp_f32_e32 v80, v84
	s_nop 0
	v_sub_f32_e32 v84, 1.0, v80
	v_pk_mul_f32 v[102:103], v[84:85], v[148:149] op_sel_hi:[0,1]
	v_pk_mul_f32 v[84:85], v[84:85], v[150:151] op_sel_hi:[0,1]
	v_pk_fma_f32 v[84:85], v[80:81], v[106:107], v[84:85] op_sel_hi:[0,1,1]
	v_pk_fma_f32 v[102:103], v[80:81], v[108:109], v[102:103] op_sel_hi:[0,1,1]
	v_lshlrev_b32_e32 v80, 16, v77
	v_exp_f32_e32 v80, v80
	v_pk_fma_f32 v[106:107], v[76:77], v[102:103], v[110:111] op_sel_hi:[0,1,1]
	v_pk_fma_f32 v[74:75], v[76:77], v[84:85], v[74:75] op_sel_hi:[0,1,1]
	v_lshlrev_b32_e32 v76, 16, v81
	v_sub_f32_e32 v108, 1.0, v80
	v_pk_mul_f32 v[110:111], v[108:109], v[150:151] op_sel_hi:[0,1]
	v_pk_mul_f32 v[108:109], v[108:109], v[148:149] op_sel_hi:[0,1]
	v_pk_fma_f32 v[96:97], v[80:81], v[96:97], v[108:109] op_sel_hi:[0,1,1]
	v_pk_fma_f32 v[94:95], v[80:81], v[94:95], v[110:111] op_sel_hi:[0,1,1]
	v_pk_fma_f32 v[74:75], v[76:77], v[94:95], v[74:75] op_sel_hi:[0,1,1]
	v_pk_fma_f32 v[106:107], v[76:77], v[96:97], v[106:107] op_sel_hi:[0,1,1]
	v_and_b32_e32 v76, 0xffff0000, v77
	v_exp_f32_e32 v76, v76
	v_and_b32_e32 v108, 0xffff0000, v81
	v_sub_f32_e32 v80, 1.0, v76
	v_pk_mul_f32 v[110:111], v[80:81], v[148:149] op_sel_hi:[0,1]
	v_pk_mul_f32 v[80:81], v[80:81], v[150:151] op_sel_hi:[0,1]
	v_pk_fma_f32 v[80:81], v[76:77], v[88:89], v[80:81] op_sel_hi:[0,1,1]
	v_pk_fma_f32 v[88:89], v[76:77], v[90:91], v[110:111] op_sel_hi:[0,1,1]
	v_pk_fma_f32 v[76:77], v[108:109], v[88:89], v[106:107] op_sel_hi:[0,1,1]
	v_pk_fma_f32 v[74:75], v[108:109], v[80:81], v[74:75] op_sel_hi:[0,1,1]
	ds_write_b128 v127, v[74:77] offset:16384
	s_waitcnt vmcnt(22)
	v_lshlrev_b32_e32 v74, 16, v66
	v_exp_f32_e32 v74, v74
	s_waitcnt vmcnt(20)
	v_lshlrev_b32_e32 v90, 16, v146
	v_and_b32_e32 v91, 0xffff0000, v146
	v_lshlrev_b32_e32 v106, 16, v147
	v_and_b32_e32 v107, 0xffff0000, v147
	v_sub_f32_e32 v76, 1.0, v74
	v_pk_mul_f32 v[110:111], v[76:77], v[90:91] op_sel_hi:[0,1]
	v_pk_mul_f32 v[76:77], v[76:77], v[106:107] op_sel_hi:[0,1]
	v_lshlrev_b32_e32 v108, 16, v70
	v_pk_fma_f32 v[76:77], v[74:75], v[92:93], v[76:77] op_sel_hi:[0,1,1]
	v_pk_fma_f32 v[74:75], v[74:75], v[100:101], v[110:111] op_sel_hi:[0,1,1]
	v_pk_fma_f32 v[92:93], v[108:109], v[74:75], 0 op_sel_hi:[0,1,0]
	v_pk_fma_f32 v[100:101], v[108:109], v[76:77], 0 op_sel_hi:[0,1,0]
	v_and_b32_e32 v108, 0xffff0000, v66
	v_and_b32_e32 v66, 0xffff0000, v70
	v_exp_f32_e32 v70, v108
	s_nop 0
	v_sub_f32_e32 v108, 1.0, v70
	v_pk_mul_f32 v[118:119], v[108:109], v[90:91] op_sel_hi:[0,1]
	v_pk_mul_f32 v[108:109], v[108:109], v[106:107] op_sel_hi:[0,1]
	v_pk_fma_f32 v[110:111], v[70:71], v[114:115], v[108:109] op_sel_hi:[0,1,1]
	v_pk_fma_f32 v[108:109], v[70:71], v[82:83], v[118:119] op_sel_hi:[0,1,1]
	v_lshlrev_b32_e32 v70, 16, v67
	v_exp_f32_e32 v70, v70
	v_pk_fma_f32 v[82:83], v[66:67], v[110:111], v[100:101] op_sel_hi:[0,1,1]
	v_pk_fma_f32 v[92:93], v[66:67], v[108:109], v[92:93] op_sel_hi:[0,1,1]
	v_lshlrev_b32_e32 v66, 16, v71
	v_sub_f32_e32 v100, 1.0, v70
	v_pk_mul_f32 v[118:119], v[100:101], v[90:91] op_sel_hi:[0,1]
	v_pk_mul_f32 v[100:101], v[100:101], v[106:107] op_sel_hi:[0,1]
	v_pk_fma_f32 v[114:115], v[70:71], v[104:105], v[100:101] op_sel_hi:[0,1,1]
	v_pk_fma_f32 v[112:113], v[70:71], v[112:113], v[118:119] op_sel_hi:[0,1,1]
	v_pk_fma_f32 v[92:93], v[66:67], v[112:113], v[92:93] op_sel_hi:[0,1,1]
	v_pk_fma_f32 v[82:83], v[66:67], v[114:115], v[82:83] op_sel_hi:[0,1,1]
	v_and_b32_e32 v67, 0xffff0000, v67
	v_exp_f32_e32 v70, v67
	v_and_b32_e32 v66, 0xffff0000, v71
	v_sub_f32_e32 v100, 1.0, v70
	v_pk_mul_f32 v[104:105], v[100:101], v[90:91] op_sel_hi:[0,1]
	v_pk_mul_f32 v[100:101], v[100:101], v[106:107] op_sel_hi:[0,1]
	v_pk_fma_f32 v[118:119], v[70:71], v[116:117], v[100:101] op_sel_hi:[0,1,1]
	v_pk_fma_f32 v[116:117], v[70:71], v[78:79], v[104:105] op_sel_hi:[0,1,1]
	v_lshlrev_b32_e32 v79, 16, v68
	v_pk_fma_f32 v[70:71], v[66:67], v[118:119], v[82:83] op_sel_hi:[0,1,1]
	v_exp_f32_e32 v82, v79
	v_pk_fma_f32 v[66:67], v[66:67], v[116:117], v[92:93] op_sel_hi:[0,1,1]
	v_lshlrev_b32_e32 v78, 16, v72
	v_sub_f32_e32 v92, 1.0, v82
	v_pk_mul_f32 v[104:105], v[92:93], v[90:91] op_sel_hi:[0,1]
	v_pk_mul_f32 v[92:93], v[92:93], v[106:107] op_sel_hi:[0,1]
	v_pk_fma_f32 v[100:101], v[82:83], v[86:87], v[92:93] op_sel_hi:[0,1,1]
	v_pk_fma_f32 v[98:99], v[82:83], v[98:99], v[104:105] op_sel_hi:[0,1,1]
	v_pk_fma_f32 v[66:67], v[78:79], v[98:99], v[66:67] op_sel_hi:[0,1,1]
	v_pk_fma_f32 v[70:71], v[78:79], v[100:101], v[70:71] op_sel_hi:[0,1,1]
	v_and_b32_e32 v78, 0xffff0000, v68
	v_and_b32_e32 v68, 0xffff0000, v72
	v_exp_f32_e32 v72, v78
	s_nop 0
	v_sub_f32_e32 v78, 1.0, v72
	v_pk_mul_f32 v[82:83], v[78:79], v[90:91] op_sel_hi:[0,1]
	v_pk_mul_f32 v[78:79], v[78:79], v[106:107] op_sel_hi:[0,1]
	v_pk_fma_f32 v[86:87], v[72:73], v[102:103], v[78:79] op_sel_hi:[0,1,1]
	v_pk_fma_f32 v[84:85], v[72:73], v[84:85], v[82:83] op_sel_hi:[0,1,1]
	v_lshlrev_b32_e32 v72, 16, v69
	v_exp_f32_e32 v72, v72
	v_pk_fma_f32 v[70:71], v[68:69], v[86:87], v[70:71] op_sel_hi:[0,1,1]
	v_pk_fma_f32 v[66:67], v[68:69], v[84:85], v[66:67] op_sel_hi:[0,1,1]
	v_lshlrev_b32_e32 v68, 16, v73
	v_sub_f32_e32 v78, 1.0, v72
	v_pk_mul_f32 v[82:83], v[78:79], v[90:91] op_sel_hi:[0,1]
	v_pk_mul_f32 v[78:79], v[78:79], v[106:107] op_sel_hi:[0,1]
	v_pk_fma_f32 v[94:95], v[72:73], v[94:95], v[82:83] op_sel_hi:[0,1,1]
	v_pk_fma_f32 v[96:97], v[72:73], v[96:97], v[78:79] op_sel_hi:[0,1,1]
	v_pk_fma_f32 v[78:79], v[68:69], v[94:95], v[66:67] op_sel_hi:[0,1,1]
	v_and_b32_e32 v66, 0xffff0000, v69
	v_exp_f32_e32 v66, v66
	v_pk_fma_f32 v[70:71], v[68:69], v[96:97], v[70:71] op_sel_hi:[0,1,1]
	v_and_b32_e32 v82, 0xffff0000, v73
	v_sub_f32_e32 v68, 1.0, v66
	v_pk_mul_f32 v[72:73], v[68:69], v[90:91] op_sel_hi:[0,1]
	v_pk_mul_f32 v[68:69], v[68:69], v[106:107] op_sel_hi:[0,1]
	v_pk_fma_f32 v[68:69], v[66:67], v[88:89], v[68:69] op_sel_hi:[0,1,1]
	v_pk_fma_f32 v[66:67], v[66:67], v[80:81], v[72:73] op_sel_hi:[0,1,1]
	v_pk_fma_f32 v[72:73], v[82:83], v[68:69], v[70:71] op_sel_hi:[0,1,1]
	v_pk_fma_f32 v[70:71], v[82:83], v[66:67], v[78:79] op_sel_hi:[0,1,1]
	ds_write_b128 v127, v[70:73] offset:24576
	v_lshl_add_u64 v[70:71], v[134:135], 0, v[130:131]
	global_store_dwordx4 v[70:71], v[74:77], off offset:-2048 sc1
	global_store_dwordx4 v[70:71], v[108:111], off offset:-1536 sc1
	global_store_dwordx4 v[70:71], v[112:115], off offset:-1024 sc1
	global_store_dwordx4 v[70:71], v[116:119], off offset:-512 sc1
	global_store_dwordx4 v[70:71], v[98:101], off sc1
	global_store_dwordx4 v[70:71], v[84:87], off offset:512 sc1
	global_store_dwordx4 v[70:71], v[94:97], off offset:1024 sc1
	global_store_dwordx4 v[70:71], v[66:69], off offset:1536 sc1
	s_waitcnt lgkmcnt(0)
	s_barrier
	ds_read2st64_b32 v[66:67], v167 offset1:2
	s_waitcnt lgkmcnt(0)
	v_add_f32_e32 v66, 0, v66
	v_add_f32_e32 v68, v66, v67
	ds_read2st64_b32 v[66:67], v167 offset0:4 offset1:6
	s_waitcnt lgkmcnt(0)
	v_add_f32_e32 v66, v68, v66
	v_add_f32_e32 v68, v66, v67
	ds_read2st64_b32 v[66:67], v167 offset0:8 offset1:10
	s_waitcnt lgkmcnt(0)
	v_add_f32_e32 v66, v68, v66
	v_add_f32_e32 v68, v66, v67
	ds_read2st64_b32 v[66:67], v167 offset0:12 offset1:14
	s_waitcnt lgkmcnt(0)
	v_add_f32_e32 v66, v68, v66
	v_add_f32_e32 v68, v66, v67
	ds_read2st64_b32 v[66:67], v167 offset0:16 offset1:18
	s_waitcnt lgkmcnt(0)
	v_add_f32_e32 v66, v68, v66
	v_add_f32_e32 v68, v66, v67
	ds_read2st64_b32 v[66:67], v167 offset0:20 offset1:22
	s_waitcnt lgkmcnt(0)
	v_add_f32_e32 v66, v68, v66
	v_add_f32_e32 v68, v66, v67
	ds_read2st64_b32 v[66:67], v167 offset0:24 offset1:26
	s_waitcnt lgkmcnt(0)
	v_add_f32_e32 v66, v68, v66
	v_add_f32_e32 v68, v66, v67
	ds_read2st64_b32 v[66:67], v167 offset0:28 offset1:30
	s_waitcnt lgkmcnt(0)
	v_add_f32_e32 v66, v68, v66
	v_add_f32_e32 v66, v66, v67
	ds_write_b32 v164, v66 offset:8192
	s_waitcnt lgkmcnt(0)
	s_barrier
	s_cbranch_scc1 .LBB0_1194
	v_lshl_add_u32 v66, s5, 9, v165
	ds_read2st64_b32 v[66:67], v66 offset0:32 offset1:33
	v_and_b32_e32 v69, 64, v221
	v_add_u32_e32 v69, 64, v69
	v_xor_b32_e32 v70, 1, v221
	v_cmp_lt_i32_e32 vcc, v70, v69
	s_waitcnt lgkmcnt(0)
	v_mul_f32_e32 v68, v67, v67
	v_fmac_f32_e32 v68, v66, v66
	v_cndmask_b32_e32 v70, v221, v70, vcc
	v_lshlrev_b32_e32 v70, 2, v70
	ds_bpermute_b32 v70, v70, v68
	s_ashr_i32 s8, s4, 31
	s_ashr_i32 s9, s5, 31
	s_add_u32 s4, s4, s5
	s_addc_u32 s5, s8, s9
	s_waitcnt lgkmcnt(0)
	v_add_f32_e32 v68, v68, v70
	v_xor_b32_e32 v70, 2, v221
	v_cmp_lt_i32_e32 vcc, v70, v69
	s_add_u32 s4, s4, 0x4000
	s_addc_u32 s5, s5, 0
	v_cndmask_b32_e32 v70, v221, v70, vcc
	v_lshlrev_b32_e32 v70, 2, v70
	ds_bpermute_b32 v70, v70, v68
	s_mul_i32 s8, s5, 0x1600
	s_mul_hi_u32 s9, s4, 0x1600
	s_add_i32 s9, s9, s8
	s_mul_i32 s8, s4, 0x1600
	s_waitcnt lgkmcnt(0)
	v_add_f32_e32 v68, v68, v70
	v_xor_b32_e32 v70, 4, v221
	v_cmp_lt_i32_e32 vcc, v70, v69
	s_add_u32 s8, s52, s8
	s_addc_u32 s9, s53, s9
	v_cndmask_b32_e32 v70, v221, v70, vcc
	v_lshlrev_b32_e32 v70, 2, v70
	ds_bpermute_b32 v70, v70, v68
	s_add_u32 s8, s8, s1
	s_addc_u32 s9, s9, 0
	s_lshl_b64 s[4:5], s[4:5], 11
	s_add_u32 s4, s14, s4
	s_waitcnt lgkmcnt(0)
	v_add_f32_e32 v68, v68, v70
	v_xor_b32_e32 v70, 8, v221
	v_cmp_lt_i32_e32 vcc, v70, v69
	s_addc_u32 s5, s15, s5
	s_add_u32 s4, s4, s1
	v_cndmask_b32_e32 v70, v221, v70, vcc
	v_lshlrev_b32_e32 v70, 2, v70
	ds_bpermute_b32 v70, v70, v68
	s_addc_u32 s5, s5, 0
	s_waitcnt lgkmcnt(0)
	v_add_f32_e32 v68, v68, v70
	v_xor_b32_e32 v70, 16, v221
	v_cmp_lt_i32_e32 vcc, v70, v69
	s_nop 1
	v_cndmask_b32_e32 v70, v221, v70, vcc
	v_lshlrev_b32_e32 v70, 2, v70
	ds_bpermute_b32 v70, v70, v68
	s_waitcnt lgkmcnt(0)
	v_add_f32_e32 v68, v68, v70
	v_xor_b32_e32 v70, 32, v221
	v_cmp_lt_i32_e32 vcc, v70, v69
	s_nop 1
	v_cndmask_b32_e32 v69, v221, v70, vcc
	v_lshlrev_b32_e32 v69, 2, v69
	ds_bpermute_b32 v69, v69, v68
	s_waitcnt lgkmcnt(0)
	v_add_f32_e32 v68, v68, v69
	v_fmamk_f32 v68, v68, 0x3c000000, v218
	v_rsq_f32_e32 v74, v68
	global_load_dword v68, v[128:129], off
	global_load_dword v75, v[128:129], off offset:256
	v_lshlrev_b32_e32 v76, 1, v126
	v_mov_b32_e32 v77, v16
	v_lshl_add_u64 v[70:71], s[8:9], 0, v[76:77]
	s_mov_b64 s[8:9], 0x1200
	v_lshl_add_u64 v[72:73], v[70:71], 0, s[8:9]
	v_add_co_u32_e32 v70, vcc, s13, v70
	s_nop 1
	v_addc_co_u32_e32 v71, vcc, 0, v71, vcc
	global_load_ushort v69, v[70:71], off offset:512
	global_load_ushort v78, v[72:73], off offset:128
	v_mul_f32_e32 v66, v66, v74
	v_mul_f32_e32 v67, v67, v74
	s_waitcnt vmcnt(0)
	v_mul_f32_e32 v66, v68, v66
	v_lshlrev_b32_e32 v69, 16, v69
	v_mul_f32_e32 v66, v66, v69
	v_cvt_pk_bf16_f32 v66, v66, v66
	global_store_short v76, v66, s[4:5] offset:1024
	v_mul_f32_e32 v67, v75, v67
	v_lshlrev_b32_e32 v78, 16, v78
	v_mul_f32_e32 v67, v67, v78
	v_cvt_pk_bf16_f32 v67, v67, v67
	global_store_short v76, v67, s[4:5] offset:1152
.LBB0_1194:
	s_waitcnt lgkmcnt(0)
	s_barrier
	s_andn2_b64 vcc, exec, s[2:3]
	s_cbranch_vccnz .LBB0_1191
	s_waitcnt vmcnt(19)
	v_lshlrev_b32_e32 v68, 16, v38
	v_exp_f32_e32 v68, v68
	v_and_b32_e32 v38, 0xffff0000, v38
	v_exp_f32_e32 v38, v38
	s_waitcnt vmcnt(17)
	v_lshlrev_b32_e32 v66, 16, v144
	v_and_b32_e32 v67, 0xffff0000, v144
	v_lshlrev_b32_e32 v70, 16, v145
	v_and_b32_e32 v71, 0xffff0000, v145
	v_sub_f32_e32 v74, 1.0, v68
	v_pk_mul_f32 v[76:77], v[74:75], v[66:67] op_sel_hi:[0,1]
	v_pk_mul_f32 v[74:75], v[74:75], v[70:71] op_sel_hi:[0,1]
	v_pk_fma_f32 v[64:65], v[64:65], v[68:69], v[74:75] op_sel_hi:[1,0,1]
	v_sub_f32_e32 v74, 1.0, v38
	v_pk_fma_f32 v[62:63], v[62:63], v[68:69], v[76:77] op_sel_hi:[1,0,1]
	v_pk_mul_f32 v[76:77], v[74:75], v[70:71] op_sel_hi:[0,1]
	v_pk_mul_f32 v[74:75], v[74:75], v[66:67] op_sel_hi:[0,1]
	v_pk_fma_f32 v[58:59], v[58:59], v[38:39], v[74:75] op_sel_hi:[1,0,1]
	v_pk_fma_f32 v[60:61], v[60:61], v[38:39], v[76:77] op_sel_hi:[1,0,1]
	v_lshlrev_b32_e32 v38, 16, v39
	v_exp_f32_e32 v38, v38
	v_lshlrev_b32_e32 v72, 16, v34
	v_pk_fma_f32 v[68:69], v[72:73], v[62:63], 0 op_sel_hi:[0,1,0]
	v_pk_fma_f32 v[72:73], v[72:73], v[64:65], 0 op_sel_hi:[0,1,0]
	v_sub_f32_e32 v74, 1.0, v38
	v_pk_mul_f32 v[76:77], v[74:75], v[66:67] op_sel_hi:[0,1]
	v_pk_mul_f32 v[74:75], v[74:75], v[70:71] op_sel_hi:[0,1]
	v_pk_fma_f32 v[56:57], v[56:57], v[38:39], v[74:75] op_sel_hi:[1,0,1]
	v_pk_fma_f32 v[54:55], v[54:55], v[38:39], v[76:77] op_sel_hi:[1,0,1]
	v_and_b32_e32 v38, 0xffff0000, v39
	v_exp_f32_e32 v38, v38
	v_and_b32_e32 v34, 0xffff0000, v34
	v_pk_fma_f32 v[72:73], v[34:35], v[60:61], v[72:73] op_sel_hi:[0,1,1]
	v_pk_fma_f32 v[68:69], v[34:35], v[58:59], v[68:69] op_sel_hi:[0,1,1]
	v_lshlrev_b32_e32 v34, 16, v35
	v_sub_f32_e32 v74, 1.0, v38
	v_pk_fma_f32 v[68:69], v[34:35], v[54:55], v[68:69] op_sel_hi:[0,1,1]
	v_pk_fma_f32 v[72:73], v[34:35], v[56:57], v[72:73] op_sel_hi:[0,1,1]
	v_and_b32_e32 v34, 0xffff0000, v35
	v_pk_mul_f32 v[76:77], v[74:75], v[70:71] op_sel_hi:[0,1]
	v_pk_mul_f32 v[74:75], v[74:75], v[66:67] op_sel_hi:[0,1]
	v_lshlrev_b32_e32 v35, 16, v40
	v_pk_fma_f32 v[50:51], v[50:51], v[38:39], v[74:75] op_sel_hi:[1,0,1]
	v_pk_fma_f32 v[38:39], v[52:53], v[38:39], v[76:77] op_sel_hi:[1,0,1]
	v_exp_f32_e32 v52, v35
	v_and_b32_e32 v40, 0xffff0000, v40
	v_exp_f32_e32 v40, v40
	v_pk_fma_f32 v[72:73], v[34:35], v[38:39], v[72:73] op_sel_hi:[0,1,1]
	v_sub_f32_e32 v74, 1.0, v52
	v_pk_mul_f32 v[76:77], v[74:75], v[66:67] op_sel_hi:[0,1]
	v_pk_mul_f32 v[74:75], v[74:75], v[70:71] op_sel_hi:[0,1]
	v_pk_fma_f32 v[34:35], v[34:35], v[50:51], v[68:69] op_sel_hi:[0,1,1]
	v_lshlrev_b32_e32 v68, 16, v36
	v_pk_fma_f32 v[48:49], v[48:49], v[52:53], v[74:75] op_sel_hi:[1,0,1]
	v_pk_fma_f32 v[46:47], v[46:47], v[52:53], v[76:77] op_sel_hi:[1,0,1]
	v_pk_fma_f32 v[52:53], v[68:69], v[48:49], v[72:73] op_sel_hi:[0,1,1]
	v_pk_fma_f32 v[34:35], v[68:69], v[46:47], v[34:35] op_sel_hi:[0,1,1]
	v_sub_f32_e32 v68, 1.0, v40
	v_pk_mul_f32 v[72:73], v[68:69], v[70:71] op_sel_hi:[0,1]
	v_pk_mul_f32 v[68:69], v[68:69], v[66:67] op_sel_hi:[0,1]
	v_pk_fma_f32 v[42:43], v[42:43], v[40:41], v[68:69] op_sel_hi:[1,0,1]
	v_pk_fma_f32 v[44:45], v[44:45], v[40:41], v[72:73] op_sel_hi:[1,0,1]
	v_lshlrev_b32_e32 v40, 16, v41
	v_exp_f32_e32 v40, v40
	v_and_b32_e32 v36, 0xffff0000, v36
	v_pk_fma_f32 v[52:53], v[36:37], v[44:45], v[52:53] op_sel_hi:[0,1,1]
	v_pk_fma_f32 v[34:35], v[36:37], v[42:43], v[34:35] op_sel_hi:[0,1,1]
	v_sub_f32_e32 v68, 1.0, v40
	v_pk_mul_f32 v[72:73], v[68:69], v[66:67] op_sel_hi:[0,1]
	v_pk_mul_f32 v[68:69], v[68:69], v[70:71] op_sel_hi:[0,1]
	v_pk_fma_f32 v[32:33], v[32:33], v[40:41], v[68:69] op_sel_hi:[1,0,1]
	v_pk_fma_f32 v[30:31], v[30:31], v[40:41], v[72:73] op_sel_hi:[1,0,1]
	v_and_b32_e32 v40, 0xffff0000, v41
	v_exp_f32_e32 v40, v40
	v_lshlrev_b32_e32 v36, 16, v37
	v_pk_fma_f32 v[34:35], v[36:37], v[30:31], v[34:35] op_sel_hi:[0,1,1]
	v_pk_fma_f32 v[52:53], v[36:37], v[32:33], v[52:53] op_sel_hi:[0,1,1]
	v_sub_f32_e32 v68, 1.0, v40
	v_pk_mul_f32 v[70:71], v[68:69], v[70:71] op_sel_hi:[0,1]
	v_pk_mul_f32 v[66:67], v[68:69], v[66:67] op_sel_hi:[0,1]
	v_and_b32_e32 v36, 0xffff0000, v37
	v_pk_fma_f32 v[66:67], v[26:27], v[40:41], v[66:67] op_sel_hi:[1,0,1]
	v_pk_fma_f32 v[40:41], v[28:29], v[40:41], v[70:71] op_sel_hi:[1,0,1]
	v_pk_fma_f32 v[26:27], v[36:37], v[66:67], v[34:35] op_sel_hi:[0,1,1]
	v_pk_fma_f32 v[28:29], v[36:37], v[40:41], v[52:53] op_sel_hi:[0,1,1]
	ds_write_b128 v127, v[26:29]
	s_waitcnt vmcnt(16)
	v_lshlrev_b32_e32 v28, 16, v22
	v_exp_f32_e32 v28, v28
	v_and_b32_e32 v22, 0xffff0000, v22
	v_exp_f32_e32 v22, v22
	s_waitcnt vmcnt(14)
	v_lshlrev_b32_e32 v26, 16, v142
	v_and_b32_e32 v27, 0xffff0000, v142
	v_lshlrev_b32_e32 v34, 16, v143
	v_and_b32_e32 v35, 0xffff0000, v143
	v_sub_f32_e32 v52, 1.0, v28
	v_pk_mul_f32 v[68:69], v[52:53], v[26:27] op_sel_hi:[0,1]
	v_pk_mul_f32 v[52:53], v[52:53], v[34:35] op_sel_hi:[0,1]
	v_pk_fma_f32 v[52:53], v[28:29], v[64:65], v[52:53] op_sel_hi:[0,1,1]
	v_sub_f32_e32 v64, 1.0, v22
	v_pk_fma_f32 v[28:29], v[28:29], v[62:63], v[68:69] op_sel_hi:[0,1,1]
	v_pk_mul_f32 v[68:69], v[64:65], v[34:35] op_sel_hi:[0,1]
	v_pk_mul_f32 v[64:65], v[64:65], v[26:27] op_sel_hi:[0,1]
	v_pk_fma_f32 v[58:59], v[22:23], v[58:59], v[64:65] op_sel_hi:[0,1,1]
	v_pk_fma_f32 v[60:61], v[22:23], v[60:61], v[68:69] op_sel_hi:[0,1,1]
	v_lshlrev_b32_e32 v22, 16, v23
	v_exp_f32_e32 v22, v22
	v_lshlrev_b32_e32 v36, 16, v18
	v_pk_fma_f32 v[62:63], v[36:37], v[28:29], 0 op_sel_hi:[0,1,0]
	v_pk_fma_f32 v[36:37], v[36:37], v[52:53], 0 op_sel_hi:[0,1,0]
	v_sub_f32_e32 v64, 1.0, v22
	v_pk_mul_f32 v[68:69], v[64:65], v[26:27] op_sel_hi:[0,1]
	v_pk_mul_f32 v[64:65], v[64:65], v[34:35] op_sel_hi:[0,1]
	v_pk_fma_f32 v[56:57], v[22:23], v[56:57], v[64:65] op_sel_hi:[0,1,1]
	v_pk_fma_f32 v[54:55], v[22:23], v[54:55], v[68:69] op_sel_hi:[0,1,1]
	v_and_b32_e32 v22, 0xffff0000, v23
	v_exp_f32_e32 v22, v22
	v_and_b32_e32 v18, 0xffff0000, v18
	v_pk_fma_f32 v[36:37], v[18:19], v[60:61], v[36:37] op_sel_hi:[0,1,1]
	v_pk_fma_f32 v[62:63], v[18:19], v[58:59], v[62:63] op_sel_hi:[0,1,1]
	v_lshlrev_b32_e32 v18, 16, v19
	v_sub_f32_e32 v64, 1.0, v22
	v_pk_fma_f32 v[62:63], v[18:19], v[54:55], v[62:63] op_sel_hi:[0,1,1]
	v_pk_fma_f32 v[36:37], v[18:19], v[56:57], v[36:37] op_sel_hi:[0,1,1]
	v_and_b32_e32 v18, 0xffff0000, v19
	v_pk_mul_f32 v[68:69], v[64:65], v[34:35] op_sel_hi:[0,1]
	v_pk_mul_f32 v[64:65], v[64:65], v[26:27] op_sel_hi:[0,1]
	v_lshlrev_b32_e32 v19, 16, v24
	v_pk_fma_f32 v[50:51], v[22:23], v[50:51], v[64:65] op_sel_hi:[0,1,1]
	v_pk_fma_f32 v[22:23], v[22:23], v[38:39], v[68:69] op_sel_hi:[0,1,1]
	v_exp_f32_e32 v38, v19
	v_and_b32_e32 v24, 0xffff0000, v24
	v_exp_f32_e32 v24, v24
	v_pk_fma_f32 v[36:37], v[18:19], v[22:23], v[36:37] op_sel_hi:[0,1,1]
	v_sub_f32_e32 v64, 1.0, v38
	v_pk_mul_f32 v[68:69], v[64:65], v[26:27] op_sel_hi:[0,1]
	v_pk_mul_f32 v[64:65], v[64:65], v[34:35] op_sel_hi:[0,1]
	v_pk_fma_f32 v[18:19], v[18:19], v[50:51], v[62:63] op_sel_hi:[0,1,1]
	v_lshlrev_b32_e32 v62, 16, v20
	v_pk_fma_f32 v[48:49], v[38:39], v[48:49], v[64:65] op_sel_hi:[0,1,1]
	v_pk_fma_f32 v[38:39], v[38:39], v[46:47], v[68:69] op_sel_hi:[0,1,1]
	v_sub_f32_e32 v46, 1.0, v24
	v_pk_fma_f32 v[18:19], v[62:63], v[38:39], v[18:19] op_sel_hi:[0,1,1]
	v_pk_fma_f32 v[36:37], v[62:63], v[48:49], v[36:37] op_sel_hi:[0,1,1]
	v_pk_mul_f32 v[62:63], v[46:47], v[34:35] op_sel_hi:[0,1]
	v_pk_mul_f32 v[46:47], v[46:47], v[26:27] op_sel_hi:[0,1]
	v_pk_fma_f32 v[42:43], v[24:25], v[42:43], v[46:47] op_sel_hi:[0,1,1]
	v_pk_fma_f32 v[44:45], v[24:25], v[44:45], v[62:63] op_sel_hi:[0,1,1]
	v_lshlrev_b32_e32 v24, 16, v25
	v_exp_f32_e32 v24, v24
	v_and_b32_e32 v20, 0xffff0000, v20
	v_pk_fma_f32 v[36:37], v[20:21], v[44:45], v[36:37] op_sel_hi:[0,1,1]
	v_pk_fma_f32 v[18:19], v[20:21], v[42:43], v[18:19] op_sel_hi:[0,1,1]
	v_sub_f32_e32 v46, 1.0, v24
	v_pk_mul_f32 v[62:63], v[46:47], v[26:27] op_sel_hi:[0,1]
	v_pk_mul_f32 v[46:47], v[46:47], v[34:35] op_sel_hi:[0,1]
	v_pk_fma_f32 v[32:33], v[24:25], v[32:33], v[46:47] op_sel_hi:[0,1,1]
	v_pk_fma_f32 v[30:31], v[24:25], v[30:31], v[62:63] op_sel_hi:[0,1,1]
	v_and_b32_e32 v24, 0xffff0000, v25
	v_exp_f32_e32 v24, v24
	v_lshlrev_b32_e32 v20, 16, v21
	v_pk_fma_f32 v[18:19], v[20:21], v[30:31], v[18:19] op_sel_hi:[0,1,1]
	v_pk_fma_f32 v[36:37], v[20:21], v[32:33], v[36:37] op_sel_hi:[0,1,1]
	v_sub_f32_e32 v20, 1.0, v24
	v_and_b32_e32 v46, 0xffff0000, v21
	v_pk_mul_f32 v[34:35], v[20:21], v[34:35] op_sel_hi:[0,1]
	v_pk_mul_f32 v[20:21], v[20:21], v[26:27] op_sel_hi:[0,1]
	v_pk_fma_f32 v[26:27], v[24:25], v[66:67], v[20:21] op_sel_hi:[0,1,1]
	v_pk_fma_f32 v[24:25], v[24:25], v[40:41], v[34:35] op_sel_hi:[0,1,1]
	v_pk_fma_f32 v[20:21], v[46:47], v[24:25], v[36:37] op_sel_hi:[0,1,1]
	v_pk_fma_f32 v[18:19], v[46:47], v[26:27], v[18:19] op_sel_hi:[0,1,1]
	ds_write_b128 v127, v[18:21] offset:8192
	s_waitcnt vmcnt(13)
	v_lshlrev_b32_e32 v20, 16, v12
	v_exp_f32_e32 v20, v20
	v_and_b32_e32 v12, 0xffff0000, v12
	v_exp_f32_e32 v12, v12
	s_waitcnt vmcnt(11)
	v_lshlrev_b32_e32 v18, 16, v140
	v_and_b32_e32 v19, 0xffff0000, v140
	v_lshlrev_b32_e32 v34, 16, v141
	v_and_b32_e32 v35, 0xffff0000, v141
	v_sub_f32_e32 v40, 1.0, v20
	v_pk_mul_f32 v[46:47], v[40:41], v[18:19] op_sel_hi:[0,1]
	v_pk_mul_f32 v[40:41], v[40:41], v[34:35] op_sel_hi:[0,1]
	v_pk_fma_f32 v[40:41], v[20:21], v[52:53], v[40:41] op_sel_hi:[0,1,1]
	v_pk_fma_f32 v[20:21], v[20:21], v[28:29], v[46:47] op_sel_hi:[0,1,1]
	v_sub_f32_e32 v46, 1.0, v12
	v_pk_mul_f32 v[52:53], v[46:47], v[34:35] op_sel_hi:[0,1]
	v_pk_mul_f32 v[46:47], v[46:47], v[18:19] op_sel_hi:[0,1]
	v_pk_fma_f32 v[46:47], v[12:13], v[58:59], v[46:47] op_sel_hi:[0,1,1]
	v_pk_fma_f32 v[52:53], v[12:13], v[60:61], v[52:53] op_sel_hi:[0,1,1]
	v_lshlrev_b32_e32 v12, 16, v13
	v_exp_f32_e32 v12, v12
	v_lshlrev_b32_e32 v36, 16, v8
	v_pk_fma_f32 v[28:29], v[36:37], v[20:21], 0 op_sel_hi:[0,1,0]
	v_pk_fma_f32 v[36:37], v[36:37], v[40:41], 0 op_sel_hi:[0,1,0]
	v_sub_f32_e32 v58, 1.0, v12
	v_pk_mul_f32 v[60:61], v[58:59], v[18:19] op_sel_hi:[0,1]
	v_pk_mul_f32 v[58:59], v[58:59], v[34:35] op_sel_hi:[0,1]
	v_pk_fma_f32 v[56:57], v[12:13], v[56:57], v[58:59] op_sel_hi:[0,1,1]
	v_pk_fma_f32 v[54:55], v[12:13], v[54:55], v[60:61] op_sel_hi:[0,1,1]
	v_and_b32_e32 v12, 0xffff0000, v13
	v_exp_f32_e32 v12, v12
	v_and_b32_e32 v8, 0xffff0000, v8
	v_pk_fma_f32 v[36:37], v[8:9], v[52:53], v[36:37] op_sel_hi:[0,1,1]
	v_pk_fma_f32 v[28:29], v[8:9], v[46:47], v[28:29] op_sel_hi:[0,1,1]
	v_lshlrev_b32_e32 v8, 16, v9
	v_sub_f32_e32 v58, 1.0, v12
	v_pk_fma_f32 v[28:29], v[8:9], v[54:55], v[28:29] op_sel_hi:[0,1,1]
	v_pk_fma_f32 v[36:37], v[8:9], v[56:57], v[36:37] op_sel_hi:[0,1,1]
	v_and_b32_e32 v8, 0xffff0000, v9
	v_pk_mul_f32 v[60:61], v[58:59], v[34:35] op_sel_hi:[0,1]
	v_pk_mul_f32 v[58:59], v[58:59], v[18:19] op_sel_hi:[0,1]
	v_lshlrev_b32_e32 v9, 16, v14
	v_pk_fma_f32 v[50:51], v[12:13], v[50:51], v[58:59] op_sel_hi:[0,1,1]
	v_pk_fma_f32 v[22:23], v[12:13], v[22:23], v[60:61] op_sel_hi:[0,1,1]
	v_exp_f32_e32 v12, v9
	v_pk_fma_f32 v[36:37], v[8:9], v[22:23], v[36:37] op_sel_hi:[0,1,1]
	v_pk_fma_f32 v[8:9], v[8:9], v[50:51], v[28:29] op_sel_hi:[0,1,1]
	v_lshlrev_b32_e32 v28, 16, v10
	v_sub_f32_e32 v58, 1.0, v12
	v_pk_mul_f32 v[60:61], v[58:59], v[18:19] op_sel_hi:[0,1]
	v_pk_mul_f32 v[58:59], v[58:59], v[34:35] op_sel_hi:[0,1]
	v_pk_fma_f32 v[48:49], v[12:13], v[48:49], v[58:59] op_sel_hi:[0,1,1]
	v_pk_fma_f32 v[38:39], v[12:13], v[38:39], v[60:61] op_sel_hi:[0,1,1]
	v_and_b32_e32 v12, 0xffff0000, v14
	v_exp_f32_e32 v12, v12
	v_pk_fma_f32 v[8:9], v[28:29], v[38:39], v[8:9] op_sel_hi:[0,1,1]
	v_pk_fma_f32 v[28:29], v[28:29], v[48:49], v[36:37] op_sel_hi:[0,1,1]
	v_and_b32_e32 v10, 0xffff0000, v10
	v_sub_f32_e32 v14, 1.0, v12
	v_pk_mul_f32 v[36:37], v[14:15], v[34:35] op_sel_hi:[0,1]
	v_pk_mul_f32 v[58:59], v[14:15], v[18:19] op_sel_hi:[0,1]
	v_pk_fma_f32 v[42:43], v[12:13], v[42:43], v[58:59] op_sel_hi:[0,1,1]
	v_pk_fma_f32 v[36:37], v[12:13], v[44:45], v[36:37] op_sel_hi:[0,1,1]
	v_lshlrev_b32_e32 v12, 16, v15
	v_exp_f32_e32 v12, v12
	v_pk_fma_f32 v[28:29], v[10:11], v[36:37], v[28:29] op_sel_hi:[0,1,1]
	v_pk_fma_f32 v[8:9], v[10:11], v[42:43], v[8:9] op_sel_hi:[0,1,1]
	v_lshlrev_b32_e32 v10, 16, v11
	v_sub_f32_e32 v14, 1.0, v12
	v_pk_mul_f32 v[44:45], v[14:15], v[18:19] op_sel_hi:[0,1]
	v_pk_mul_f32 v[58:59], v[14:15], v[34:35] op_sel_hi:[0,1]
	v_pk_fma_f32 v[58:59], v[12:13], v[32:33], v[58:59] op_sel_hi:[0,1,1]
	v_pk_fma_f32 v[44:45], v[12:13], v[30:31], v[44:45] op_sel_hi:[0,1,1]
	v_and_b32_e32 v12, 0xffff0000, v15
	v_exp_f32_e32 v12, v12
	v_pk_fma_f32 v[8:9], v[10:11], v[44:45], v[8:9] op_sel_hi:[0,1,1]
	v_pk_fma_f32 v[14:15], v[10:11], v[58:59], v[28:29] op_sel_hi:[0,1,1]
	v_and_b32_e32 v28, 0xffff0000, v11
	v_sub_f32_e32 v10, 1.0, v12
	v_pk_mul_f32 v[30:31], v[10:11], v[34:35] op_sel_hi:[0,1]
	v_pk_mul_f32 v[10:11], v[10:11], v[18:19] op_sel_hi:[0,1]
	v_pk_fma_f32 v[60:61], v[12:13], v[26:27], v[10:11] op_sel_hi:[0,1,1]
	v_pk_fma_f32 v[62:63], v[12:13], v[24:25], v[30:31] op_sel_hi:[0,1,1]
	v_pk_fma_f32 v[10:11], v[28:29], v[62:63], v[14:15] op_sel_hi:[0,1,1]
	v_pk_fma_f32 v[8:9], v[28:29], v[60:61], v[8:9] op_sel_hi:[0,1,1]
	ds_write_b128 v127, v[8:11] offset:16384
	s_waitcnt vmcnt(10)
	v_lshlrev_b32_e32 v8, 16, v4
	v_exp_f32_e32 v8, v8
	v_and_b32_e32 v4, 0xffff0000, v4
	v_exp_f32_e32 v4, v4
	s_waitcnt vmcnt(8)
	v_lshlrev_b32_e32 v64, 16, v138
	v_and_b32_e32 v65, 0xffff0000, v138
	v_lshlrev_b32_e32 v66, 16, v139
	v_and_b32_e32 v67, 0xffff0000, v139
	v_sub_f32_e32 v10, 1.0, v8
	v_pk_mul_f32 v[14:15], v[10:11], v[64:65] op_sel_hi:[0,1]
	v_pk_mul_f32 v[10:11], v[10:11], v[66:67] op_sel_hi:[0,1]
	v_lshlrev_b32_e32 v12, 16, v0
	v_pk_fma_f32 v[10:11], v[8:9], v[40:41], v[10:11] op_sel_hi:[0,1,1]
	v_pk_fma_f32 v[8:9], v[8:9], v[20:21], v[14:15] op_sel_hi:[0,1,1]
	v_pk_fma_f32 v[18:19], v[12:13], v[8:9], 0 op_sel_hi:[0,1,0]
	v_pk_fma_f32 v[20:21], v[12:13], v[10:11], 0 op_sel_hi:[0,1,0]
	v_sub_f32_e32 v12, 1.0, v4
	v_pk_mul_f32 v[24:25], v[12:13], v[64:65] op_sel_hi:[0,1]
	v_pk_mul_f32 v[12:13], v[12:13], v[66:67] op_sel_hi:[0,1]
	v_pk_fma_f32 v[14:15], v[4:5], v[52:53], v[12:13] op_sel_hi:[0,1,1]
	v_pk_fma_f32 v[12:13], v[4:5], v[46:47], v[24:25] op_sel_hi:[0,1,1]
	v_lshlrev_b32_e32 v4, 16, v5
	v_exp_f32_e32 v4, v4
	v_and_b32_e32 v0, 0xffff0000, v0
	v_pk_fma_f32 v[26:27], v[0:1], v[12:13], v[18:19] op_sel_hi:[0,1,1]
	v_pk_fma_f32 v[24:25], v[0:1], v[14:15], v[20:21] op_sel_hi:[0,1,1]
	v_sub_f32_e32 v18, 1.0, v4
	v_pk_mul_f32 v[28:29], v[18:19], v[64:65] op_sel_hi:[0,1]
	v_pk_mul_f32 v[18:19], v[18:19], v[66:67] op_sel_hi:[0,1]
	v_pk_fma_f32 v[20:21], v[4:5], v[56:57], v[18:19] op_sel_hi:[0,1,1]
	v_pk_fma_f32 v[18:19], v[4:5], v[54:55], v[28:29] op_sel_hi:[0,1,1]
	v_and_b32_e32 v4, 0xffff0000, v5
	v_exp_f32_e32 v4, v4
	v_lshlrev_b32_e32 v0, 16, v1
	v_pk_fma_f32 v[28:29], v[0:1], v[20:21], v[24:25] op_sel_hi:[0,1,1]
	v_pk_fma_f32 v[26:27], v[0:1], v[18:19], v[26:27] op_sel_hi:[0,1,1]
	v_sub_f32_e32 v24, 1.0, v4
	v_and_b32_e32 v0, 0xffff0000, v1
	v_pk_mul_f32 v[30:31], v[24:25], v[64:65] op_sel_hi:[0,1]
	v_pk_mul_f32 v[24:25], v[24:25], v[66:67] op_sel_hi:[0,1]
	v_lshlrev_b32_e32 v1, 16, v6
	v_pk_fma_f32 v[24:25], v[4:5], v[22:23], v[24:25] op_sel_hi:[0,1,1]
	v_pk_fma_f32 v[22:23], v[4:5], v[50:51], v[30:31] op_sel_hi:[0,1,1]
	v_exp_f32_e32 v4, v1
	v_pk_fma_f32 v[30:31], v[0:1], v[24:25], v[28:29] op_sel_hi:[0,1,1]
	v_pk_fma_f32 v[0:1], v[0:1], v[22:23], v[26:27] op_sel_hi:[0,1,1]
	v_lshlrev_b32_e32 v32, 16, v2
	v_sub_f32_e32 v26, 1.0, v4
	v_pk_mul_f32 v[34:35], v[26:27], v[64:65] op_sel_hi:[0,1]
	v_pk_mul_f32 v[26:27], v[26:27], v[66:67] op_sel_hi:[0,1]
	v_pk_fma_f32 v[28:29], v[4:5], v[48:49], v[26:27] op_sel_hi:[0,1,1]
	v_pk_fma_f32 v[26:27], v[4:5], v[38:39], v[34:35] op_sel_hi:[0,1,1]
	v_and_b32_e32 v4, 0xffff0000, v6
	v_exp_f32_e32 v4, v4
	v_pk_fma_f32 v[0:1], v[32:33], v[26:27], v[0:1] op_sel_hi:[0,1,1]
	v_pk_fma_f32 v[34:35], v[32:33], v[28:29], v[30:31] op_sel_hi:[0,1,1]
	v_and_b32_e32 v2, 0xffff0000, v2
	v_sub_f32_e32 v6, 1.0, v4
	v_pk_mul_f32 v[30:31], v[6:7], v[64:65] op_sel_hi:[0,1]
	v_pk_mul_f32 v[32:33], v[6:7], v[66:67] op_sel_hi:[0,1]
	v_pk_fma_f32 v[32:33], v[4:5], v[36:37], v[32:33] op_sel_hi:[0,1,1]
	v_pk_fma_f32 v[30:31], v[4:5], v[42:43], v[30:31] op_sel_hi:[0,1,1]
	v_lshlrev_b32_e32 v4, 16, v7
	v_exp_f32_e32 v4, v4
	v_pk_fma_f32 v[38:39], v[2:3], v[32:33], v[34:35] op_sel_hi:[0,1,1]
	v_pk_fma_f32 v[0:1], v[2:3], v[30:31], v[0:1] op_sel_hi:[0,1,1]
	v_lshlrev_b32_e32 v2, 16, v3
	v_sub_f32_e32 v6, 1.0, v4
	v_pk_mul_f32 v[34:35], v[6:7], v[64:65] op_sel_hi:[0,1]
	v_pk_mul_f32 v[36:37], v[6:7], v[66:67] op_sel_hi:[0,1]
	v_pk_fma_f32 v[36:37], v[4:5], v[58:59], v[36:37] op_sel_hi:[0,1,1]
	v_pk_fma_f32 v[34:35], v[4:5], v[44:45], v[34:35] op_sel_hi:[0,1,1]
	v_and_b32_e32 v4, 0xffff0000, v7
	v_exp_f32_e32 v4, v4
	v_pk_fma_f32 v[40:41], v[2:3], v[34:35], v[0:1] op_sel_hi:[0,1,1]
	v_pk_fma_f32 v[6:7], v[2:3], v[36:37], v[38:39] op_sel_hi:[0,1,1]
	v_and_b32_e32 v38, 0xffff0000, v3
	v_sub_f32_e32 v0, 1.0, v4
	v_pk_mul_f32 v[42:43], v[0:1], v[64:65] op_sel_hi:[0,1]
	v_pk_mul_f32 v[0:1], v[0:1], v[66:67] op_sel_hi:[0,1]
	v_pk_fma_f32 v[2:3], v[4:5], v[62:63], v[0:1] op_sel_hi:[0,1,1]
	v_pk_fma_f32 v[0:1], v[4:5], v[60:61], v[42:43] op_sel_hi:[0,1,1]
	s_ashr_i32 s1, s0, 31
	v_pk_fma_f32 v[6:7], v[38:39], v[2:3], v[6:7] op_sel_hi:[0,1,1]
	v_pk_fma_f32 v[4:5], v[38:39], v[0:1], v[40:41] op_sel_hi:[0,1,1]
	s_lshl_b64 s[2:3], s[0:1], 16
	ds_write_b128 v127, v[4:7] offset:24576
	v_lshl_add_u64 v[4:5], v[124:125], 0, s[2:3]
	global_store_dwordx4 v[4:5], v[8:11], off sc1
	global_store_dwordx4 v[4:5], v[12:15], off offset:512 sc1
	global_store_dwordx4 v[4:5], v[18:21], off offset:1024 sc1
	global_store_dwordx4 v[4:5], v[22:25], off offset:1536 sc1
	global_store_dwordx4 v[4:5], v[26:29], off offset:2048 sc1
	global_store_dwordx4 v[4:5], v[30:33], off offset:2560 sc1
	global_store_dwordx4 v[4:5], v[34:37], off offset:3072 sc1
	global_store_dwordx4 v[4:5], v[0:3], off offset:3584 sc1
	s_waitcnt lgkmcnt(0)
	s_barrier
	ds_read2st64_b32 v[0:1], v167 offset1:2
	ds_read2st64_b32 v[2:3], v167 offset0:4 offset1:6
	ds_read2st64_b32 v[4:5], v167 offset0:8 offset1:10
	v_readfirstlane_b32 s1, v17
	s_ashr_i32 s1, s1, 6
	s_waitcnt lgkmcnt(2)
	v_add_f32_e32 v0, 0, v0
	v_add_f32_e32 v0, v0, v1
	s_waitcnt lgkmcnt(1)
	v_add_f32_e32 v2, v0, v2
	ds_read2st64_b32 v[0:1], v167 offset0:12 offset1:14
	v_add_f32_e32 v2, v2, v3
	s_waitcnt lgkmcnt(1)
	v_add_f32_e32 v4, v2, v4
	ds_read2st64_b32 v[2:3], v167 offset0:16 offset1:18
	v_add_f32_e32 v4, v4, v5
	s_waitcnt lgkmcnt(1)
	v_add_f32_e32 v0, v4, v0
	v_add_f32_e32 v4, v0, v1
	ds_read2st64_b32 v[0:1], v167 offset0:20 offset1:22
	s_waitcnt lgkmcnt(1)
	v_add_f32_e32 v2, v4, v2
	ds_read2st64_b32 v[4:5], v167 offset0:24 offset1:26
	v_add_f32_e32 v6, v2, v3
	ds_read2st64_b32 v[2:3], v167 offset0:28 offset1:30
	s_waitcnt lgkmcnt(2)
	v_add_f32_e32 v0, v6, v0
	v_add_f32_e32 v0, v0, v1
	s_waitcnt lgkmcnt(1)
	v_add_f32_e32 v0, v0, v4
	v_add_f32_e32 v0, v0, v5
	s_waitcnt lgkmcnt(0)
	v_add_f32_e32 v0, v0, v2
	v_add_f32_e32 v0, v0, v3
	ds_write_b32 v164, v0 offset:8192
	s_waitcnt lgkmcnt(0)
	s_barrier
	s_cmp_gt_i32 s1, 3
	s_cbranch_scc1 .LBB0_1190
	v_lshl_add_u32 v0, s1, 9, v165
	ds_read2st64_b32 v[0:1], v0 offset0:32 offset1:33
	v_and_b32_e32 v3, 64, v221
	v_add_u32_e32 v3, 64, v3
	v_xor_b32_e32 v4, 1, v221
	v_cmp_lt_i32_e32 vcc, v4, v3
	s_waitcnt lgkmcnt(0)
	v_mul_f32_e32 v2, v1, v1
	v_fmac_f32_e32 v2, v0, v0
	v_cndmask_b32_e32 v4, v221, v4, vcc
	v_lshlrev_b32_e32 v4, 2, v4
	ds_bpermute_b32 v4, v4, v2
	s_and_b32 s0, s0, -4
	s_ashr_i32 s2, s0, 31
	s_ashr_i32 s3, s1, 31
	s_add_u32 s0, s0, s1
	s_waitcnt lgkmcnt(0)
	v_add_f32_e32 v2, v2, v4
	v_xor_b32_e32 v4, 2, v221
	v_cmp_lt_i32_e32 vcc, v4, v3
	s_addc_u32 s1, s2, s3
	s_add_u32 s0, s0, 0x4000
	v_cndmask_b32_e32 v4, v221, v4, vcc
	v_lshlrev_b32_e32 v4, 2, v4
	ds_bpermute_b32 v4, v4, v2
	s_addc_u32 s1, s1, 0
	s_mul_i32 s2, s1, 0x1600
	s_mul_hi_u32 s3, s0, 0x1600
	s_add_i32 s3, s3, s2
	s_waitcnt lgkmcnt(0)
	v_add_f32_e32 v2, v2, v4
	v_xor_b32_e32 v4, 4, v221
	v_cmp_lt_i32_e32 vcc, v4, v3
	s_mul_i32 s2, s0, 0x1600
	s_add_u32 s4, s52, s2
	v_cndmask_b32_e32 v4, v221, v4, vcc
	v_lshlrev_b32_e32 v4, 2, v4
	ds_bpermute_b32 v4, v4, v2
	s_addc_u32 s3, s53, s3
	s_add_i32 s2, s33, s6
	s_and_b32 s2, s2, 0x180
	s_lshl_b32 s2, s2, 1
	s_waitcnt lgkmcnt(0)
	v_add_f32_e32 v2, v2, v4
	v_xor_b32_e32 v4, 8, v221
	v_cmp_lt_i32_e32 vcc, v4, v3
	s_add_u32 s4, s4, s2
	s_addc_u32 s5, s3, 0
	v_cndmask_b32_e32 v4, v221, v4, vcc
	v_lshlrev_b32_e32 v4, 2, v4
	ds_bpermute_b32 v4, v4, v2
	s_lshl_b64 s[0:1], s[0:1], 11
	s_add_u32 s0, s14, s0
	s_addc_u32 s1, s15, s1
	s_add_u32 s0, s0, s2
	s_waitcnt lgkmcnt(0)
	v_add_f32_e32 v2, v2, v4
	v_xor_b32_e32 v4, 16, v221
	v_cmp_lt_i32_e32 vcc, v4, v3
	s_addc_u32 s1, s1, 0
	s_nop 0
	v_cndmask_b32_e32 v4, v221, v4, vcc
	v_lshlrev_b32_e32 v4, 2, v4
	ds_bpermute_b32 v4, v4, v2
	s_waitcnt lgkmcnt(0)
	v_add_f32_e32 v2, v2, v4
	v_xor_b32_e32 v4, 32, v221
	v_cmp_lt_i32_e32 vcc, v4, v3
	s_nop 1
	v_cndmask_b32_e32 v3, v221, v4, vcc
	v_lshlrev_b32_e32 v3, 2, v3
	ds_bpermute_b32 v3, v3, v2
	s_waitcnt lgkmcnt(0)
	v_add_f32_e32 v2, v2, v3
	v_fmamk_f32 v2, v2, 0x3c000000, v218
	v_rsq_f32_e32 v8, v2
	global_load_dword v2, v[128:129], off
	global_load_dword v9, v[128:129], off offset:256
	v_lshlrev_b32_e32 v10, 1, v126
	v_mov_b32_e32 v11, v16
	v_lshl_add_u64 v[4:5], s[4:5], 0, v[10:11]
	s_mov_b64 s[4:5], 0x1200
	v_lshl_add_u64 v[6:7], v[4:5], 0, s[4:5]
	v_add_co_u32_e32 v4, vcc, s13, v4
	s_nop 1
	v_addc_co_u32_e32 v5, vcc, 0, v5, vcc
	global_load_ushort v3, v[4:5], off offset:512
	global_load_ushort v12, v[6:7], off offset:128
	v_mul_f32_e32 v0, v0, v8
	v_mul_f32_e32 v1, v1, v8
	s_waitcnt vmcnt(0)
	v_mul_f32_e32 v0, v2, v0
	v_lshlrev_b32_e32 v3, 16, v3
	v_mul_f32_e32 v0, v0, v3
	v_cvt_pk_bf16_f32 v0, v0, v0
	global_store_short v10, v0, s[0:1] offset:1024
	v_mul_f32_e32 v1, v9, v1
	v_lshlrev_b32_e32 v12, 16, v12
	v_mul_f32_e32 v1, v1, v12
	v_cvt_pk_bf16_f32 v1, v1, v1
	global_store_short v10, v1, s[0:1] offset:1152
	s_branch .LBB0_1190
